# non-temporal hint on the read-once loads of the gated-DeltaNet output-norm loop (P12), so the MIX rows it writes stay cached for the following out-proj
# speedup vs baseline: 1.0019x; 1.0019x over previous
.LBB0_2592:
	s_ashr_i64 s[10:11], s[4:5], 3
	s_bfe_u32 s14, s4, 0x20001
	s_mul_i32 s16, s11, 0xaaaaaaab
	s_mul_hi_u32 s17, s10, 0xaaaaaaab
	s_mul_hi_u32 s15, s11, 0xaaaaaaab
	s_add_u32 s16, s16, s17
	s_mul_i32 s13, s10, 0x2aaaaaaa
	s_addc_u32 s15, s15, 0
	s_mul_hi_u32 s12, s10, 0x2aaaaaaa
	s_add_u32 s13, s13, s16
	s_addc_u32 s12, s12, 0
	s_add_u32 s12, s15, s12
	s_mul_hi_u32 s18, s11, 0x2aaaaaaa
	s_mul_i32 s11, s11, 0x2aaaaaaa
	s_addc_u32 s13, 0, 0
	s_add_u32 s11, s11, s12
	s_addc_u32 s12, s18, s13
	s_ashr_i32 s13, s5, 31
	s_mul_i32 s15, s13, 0x2aaaaaaa
	s_mul_hi_u32 s16, s13, 0xaaaaaaab
	s_mul_i32 s13, s13, 0xaaaaaaab
	s_add_i32 s15, s16, s15
	s_add_i32 s15, s15, s13
	s_add_u32 s11, s11, s13
	s_addc_u32 s13, s12, s15
	s_lshr_b32 s12, s13, 31
	s_add_u32 s12, s11, s12
	v_lshl_or_b32 v0, s14, 4, v36
	s_addc_u32 s13, s13, 0
	s_mul_i32 s11, s12, 6
	s_lshl_b32 s14, s14, 2
	v_lshrrev_b32_e32 v0, 3, v0
	s_sub_i32 s10, s10, s11
	s_lshl_b64 s[24:25], s[12:13], 6
	s_or_b32 s11, s14, s1
	v_or_b32_e32 v0, s24, v0
	s_lshl_b32 s20, s10, 7
	s_or_b32 s24, s24, s11
	s_mul_i32 s31, s25, 0x1a00
	s_ashr_i32 s21, s20, 31
	s_mul_hi_u32 s10, s24, 0x1a00
	v_mad_u64_u32 v[0:1], s[34:35], v0, s3, v[14:15]
	s_mul_i32 s12, s24, 0x1a00
	s_lshl_b64 s[20:21], s[20:21], 1
	s_add_i32 s10, s10, s31
	v_add_u32_e32 v1, s31, v1
	s_add_u32 s12, s6, s12
	v_lshl_add_u64 v[0:1], v[0:1], 0, s[20:21]
	s_addc_u32 s10, s7, s10
	v_lshl_add_u64 v[0:1], v[0:1], 0, v[10:11]
	s_add_u32 s34, s12, s20
	v_lshl_add_u64 v[22:23], v[0:1], 0, s[8:9]
	s_addc_u32 s35, s10, s21
	s_or_b32 s26, s24, 1
	global_load_dwordx4 v[0:3], v[22:23], off nt
	global_load_dwordx4 v[4:7], v[22:23], off offset:32 nt
	v_lshl_add_u64 v[22:23], s[34:35], 0, v[16:17]
	s_mul_hi_u32 s10, s26, 0x1a00
	s_mul_i32 s12, s26, 0x1a00
	v_add_co_u32_e32 v22, vcc, s28, v22
	s_add_i32 s10, s10, s31
	s_nop 0
	v_addc_co_u32_e32 v23, vcc, 0, v23, vcc
	s_add_u32 s12, s6, s12
	global_load_dword v52, v[22:23], off offset:512 nt
	s_addc_u32 s10, s7, s10
	s_add_u32 s34, s12, s20
	s_addc_u32 s35, s10, s21
	s_or_b32 s22, s24, 2
	s_mul_hi_u32 s10, s22, 0x1a00
	v_lshl_add_u64 v[22:23], s[34:35], 0, v[16:17]
	s_mul_i32 s12, s22, 0x1a00
	s_add_i32 s10, s10, s31
	v_add_co_u32_e32 v22, vcc, s28, v22
	s_add_u32 s12, s6, s12
	s_nop 0
	v_addc_co_u32_e32 v23, vcc, 0, v23, vcc
	s_addc_u32 s10, s7, s10
	global_load_dword v49, v[22:23], off offset:512 nt
	s_add_u32 s34, s12, s20
	s_addc_u32 s35, s10, s21
	s_or_b32 s18, s24, 3
	s_mul_hi_u32 s10, s18, 0x1a00
	v_lshl_add_u64 v[22:23], s[34:35], 0, v[16:17]
	s_mul_i32 s12, s18, 0x1a00
	s_add_i32 s10, s10, s31
	v_add_co_u32_e32 v22, vcc, s28, v22
	s_add_u32 s12, s6, s12
	s_nop 0
	v_addc_co_u32_e32 v23, vcc, 0, v23, vcc
	s_addc_u32 s10, s7, s10
	global_load_dword v48, v[22:23], off offset:512 nt
	s_add_u32 s34, s12, s20
	s_addc_u32 s35, s10, s21
	s_or_b32 s16, s24, 16
	s_mul_hi_u32 s10, s16, 0x1a00
	s_mul_i32 s12, s16, 0x1a00
	s_add_i32 s10, s10, s31
	v_lshl_add_u64 v[22:23], s[34:35], 0, v[16:17]
	s_add_u32 s12, s6, s12
	v_add_co_u32_e32 v22, vcc, s28, v22
	s_addc_u32 s10, s7, s10
	s_nop 0
	v_addc_co_u32_e32 v23, vcc, 0, v23, vcc
	s_add_u32 s34, s12, s20
	global_load_dword v47, v[22:23], off offset:512 nt
	s_addc_u32 s35, s10, s21
	s_or_b32 s14, s24, 17
	s_mul_hi_u32 s10, s14, 0x1a00
	s_mul_i32 s12, s14, 0x1a00
	s_add_i32 s10, s10, s31
	v_lshl_add_u64 v[22:23], s[34:35], 0, v[16:17]
	s_add_u32 s12, s6, s12
	v_add_co_u32_e32 v22, vcc, s28, v22
	s_addc_u32 s10, s7, s10
	s_nop 0
	v_addc_co_u32_e32 v23, vcc, 0, v23, vcc
	s_add_u32 s34, s12, s20
	global_load_dword v46, v[22:23], off offset:512 nt
	s_addc_u32 s35, s10, s21
	s_or_b32 s12, s24, 18
	s_mul_hi_u32 s10, s12, 0x1a00
	v_lshl_add_u64 v[22:23], s[34:35], 0, v[16:17]
	s_mul_i32 s33, s12, 0x1a00
	s_add_i32 s10, s10, s31
	v_add_co_u32_e32 v22, vcc, s28, v22
	s_add_u32 s33, s6, s33
	s_nop 0
	v_addc_co_u32_e32 v23, vcc, 0, v23, vcc
	s_addc_u32 s10, s7, s10
	global_load_dword v45, v[22:23], off offset:512 nt
	s_add_u32 s34, s33, s20
	s_addc_u32 s35, s10, s21
	s_or_b32 s10, s24, 19
	v_lshl_add_u64 v[22:23], s[34:35], 0, v[16:17]
	s_mul_hi_u32 s33, s10, 0x1a00
	s_mul_i32 s34, s10, 0x1a00
	v_add_co_u32_e32 v22, vcc, s28, v22
	s_add_i32 s33, s33, s31
	s_nop 0
	v_addc_co_u32_e32 v23, vcc, 0, v23, vcc
	s_add_u32 s31, s6, s34
	global_load_dword v44, v[22:23], off offset:512 nt
	s_addc_u32 s33, s7, s33
	v_lshl_add_u64 v[20:21], v[12:13], 0, s[20:21]
	s_add_u32 s20, s31, s20
	s_addc_u32 s21, s33, s21
	v_lshl_add_u64 v[50:51], s[20:21], 0, v[16:17]
	v_add_co_u32_e32 v50, vcc, s28, v50
	s_waitcnt vmcnt(7)
	v_lshlrev_b32_e32 v53, 16, v4
	v_addc_co_u32_e32 v51, vcc, 0, v51, vcc
	global_load_dword v50, v[50:51], off offset:512 nt
	v_and_b32_e32 v4, 0xffff0000, v4
	v_lshlrev_b32_e32 v55, 16, v5
	v_lshlrev_b32_e32 v57, 16, v6
	v_and_b32_e32 v6, 0xffff0000, v6
	v_lshlrev_b32_e32 v51, 16, v0
	v_and_b32_e32 v0, 0xffff0000, v0
	v_lshlrev_b32_e32 v54, 16, v1
	v_and_b32_e32 v5, 0xffff0000, v5
	v_lshlrev_b32_e32 v56, 16, v2
	v_and_b32_e32 v2, 0xffff0000, v2
	v_lshlrev_b32_e32 v59, 16, v7
	v_mul_f32_e32 v60, v53, v53
	v_mul_f32_e32 v61, v4, v4
	v_mul_f32_e32 v62, v55, v55
	v_mul_f32_e32 v65, v6, v6
	v_and_b32_e32 v1, 0xffff0000, v1
	v_lshlrev_b32_e32 v58, 16, v3
	v_and_b32_e32 v7, 0xffff0000, v7
	v_mul_f32_e32 v63, v5, v5
	v_mul_f32_e32 v64, v57, v57
	v_mul_f32_e32 v66, v59, v59
	v_fmac_f32_e32 v60, v51, v51
	v_fmac_f32_e32 v61, v0, v0
	v_fmac_f32_e32 v62, v54, v54
	v_fmac_f32_e32 v65, v2, v2
	v_and_b32_e32 v3, 0xffff0000, v3
	v_mul_f32_e32 v67, v7, v7
	v_fmac_f32_e32 v63, v1, v1
	v_fmac_f32_e32 v64, v56, v56
	v_fmac_f32_e32 v66, v58, v58
	ds_bpermute_b32 v68, v37, v60
	s_waitcnt vmcnt(7)
	v_lshlrev_b32_e32 v69, 16, v52
	ds_bpermute_b32 v70, v37, v61
	ds_bpermute_b32 v71, v37, v62
	ds_bpermute_b32 v74, v37, v65
	v_fmac_f32_e32 v67, v3, v3
	v_and_b32_e32 v52, 0xffff0000, v52
	ds_bpermute_b32 v72, v37, v63
	ds_bpermute_b32 v73, v37, v64
	ds_bpermute_b32 v75, v37, v66
	v_mul_f32_e32 v77, 0xbfb8aa3b, v69
	ds_bpermute_b32 v76, v37, v67
	v_mul_f32_e32 v78, 0xbfb8aa3b, v52
	v_exp_f32_e32 v77, v77
	v_exp_f32_e32 v78, v78
	s_waitcnt lgkmcnt(7)
	v_add_f32_e32 v60, v60, v68
	s_waitcnt lgkmcnt(6)
	v_add_f32_e32 v61, v61, v70
	s_waitcnt lgkmcnt(5)
	v_add_f32_e32 v62, v62, v71
	s_waitcnt lgkmcnt(4)
	v_add_f32_e32 v65, v65, v74
	s_waitcnt lgkmcnt(3)
	v_add_f32_e32 v63, v63, v72
	s_waitcnt lgkmcnt(2)
	v_add_f32_e32 v64, v64, v73
	s_waitcnt lgkmcnt(1)
	v_add_f32_e32 v66, v66, v75
	ds_bpermute_b32 v68, v38, v60
	v_add_f32_e32 v70, 1.0, v77
	ds_bpermute_b32 v72, v38, v61
	ds_bpermute_b32 v74, v38, v62
	ds_bpermute_b32 v77, v38, v65
	s_waitcnt lgkmcnt(4)
	v_add_f32_e32 v67, v67, v76
	v_add_f32_e32 v71, 1.0, v78
	s_waitcnt vmcnt(6)
	v_lshlrev_b32_e32 v73, 16, v49
	v_and_b32_e32 v49, 0xffff0000, v49
	ds_bpermute_b32 v75, v38, v63
	ds_bpermute_b32 v76, v38, v64
	ds_bpermute_b32 v78, v38, v66
	ds_bpermute_b32 v79, v38, v67
	v_rcp_f32_e32 v70, v70
	v_mul_f32_e32 v80, 0xbfb8aa3b, v73
	v_mul_f32_e32 v81, 0xbfb8aa3b, v49
	v_rcp_f32_e32 v71, v71
	v_exp_f32_e32 v80, v80
	v_exp_f32_e32 v81, v81
	s_waitcnt lgkmcnt(7)
	v_add_f32_e32 v60, v60, v68
	s_waitcnt lgkmcnt(6)
	v_add_f32_e32 v61, v61, v72
	s_waitcnt lgkmcnt(5)
	v_add_f32_e32 v62, v62, v74
	s_waitcnt lgkmcnt(4)
	v_add_f32_e32 v65, v65, v77
	v_mul_f32_e32 v68, v70, v69
	s_waitcnt lgkmcnt(3)
	v_add_f32_e32 v63, v63, v75
	s_waitcnt lgkmcnt(2)
	v_add_f32_e32 v64, v64, v76
	s_waitcnt lgkmcnt(1)
	v_add_f32_e32 v66, v66, v78
	ds_bpermute_b32 v69, v39, v60
	ds_bpermute_b32 v70, v39, v61
	ds_bpermute_b32 v74, v39, v62
	ds_bpermute_b32 v78, v39, v65
	v_mul_f32_e32 v52, v71, v52
	s_waitcnt lgkmcnt(4)
	v_add_f32_e32 v67, v67, v79
	v_add_f32_e32 v71, 1.0, v80
	v_add_f32_e32 v72, 1.0, v81
	s_waitcnt vmcnt(5)
	v_lshlrev_b32_e32 v75, 16, v48
	ds_bpermute_b32 v76, v39, v63
	ds_bpermute_b32 v77, v39, v64
	ds_bpermute_b32 v79, v39, v66
	v_and_b32_e32 v48, 0xffff0000, v48
	ds_bpermute_b32 v80, v39, v67
	v_rcp_f32_e32 v71, v71
	v_rcp_f32_e32 v72, v72
	v_mul_f32_e32 v81, 0xbfb8aa3b, v75
	v_mul_f32_e32 v82, 0xbfb8aa3b, v48
	v_exp_f32_e32 v81, v81
	v_exp_f32_e32 v82, v82
	s_waitcnt lgkmcnt(7)
	v_add_f32_e32 v60, v60, v69
	s_waitcnt lgkmcnt(6)
	v_add_f32_e32 v61, v61, v70
	s_waitcnt lgkmcnt(5)
	v_add_f32_e32 v62, v62, v74
	s_waitcnt lgkmcnt(4)
	v_add_f32_e32 v65, v65, v78
	v_mul_f32_e32 v69, v71, v73
	v_mul_f32_e32 v49, v72, v49
	s_waitcnt lgkmcnt(3)
	v_add_f32_e32 v63, v63, v76
	s_waitcnt lgkmcnt(2)
	v_add_f32_e32 v64, v64, v77
	s_waitcnt lgkmcnt(1)
	v_add_f32_e32 v66, v66, v79
	ds_bpermute_b32 v70, v40, v60
	ds_bpermute_b32 v71, v40, v61
	ds_bpermute_b32 v72, v40, v62
	ds_bpermute_b32 v79, v40, v65
	s_waitcnt lgkmcnt(4)
	v_add_f32_e32 v67, v67, v80
	v_add_f32_e32 v73, 1.0, v81
	ds_bpermute_b32 v76, v40, v63
	ds_bpermute_b32 v78, v40, v64
	ds_bpermute_b32 v80, v40, v66
	v_add_f32_e32 v74, 1.0, v82
	s_waitcnt vmcnt(4)
	v_lshlrev_b32_e32 v77, 16, v47
	v_and_b32_e32 v47, 0xffff0000, v47
	v_rcp_f32_e32 v73, v73
	ds_bpermute_b32 v81, v40, v67
	v_rcp_f32_e32 v74, v74
	v_mul_f32_e32 v82, 0xbfb8aa3b, v77
	v_mul_f32_e32 v83, 0xbfb8aa3b, v47
	v_exp_f32_e32 v82, v82
	v_exp_f32_e32 v83, v83
	s_waitcnt lgkmcnt(7)
	v_add_f32_e32 v60, v60, v70
	s_waitcnt lgkmcnt(6)
	v_add_f32_e32 v61, v61, v71
	s_waitcnt lgkmcnt(5)
	v_add_f32_e32 v62, v62, v72
	s_waitcnt lgkmcnt(4)
	v_add_f32_e32 v65, v65, v79
	v_mul_f32_e32 v70, v73, v75
	s_waitcnt lgkmcnt(3)
	v_add_f32_e32 v63, v63, v76
	s_waitcnt lgkmcnt(2)
	v_add_f32_e32 v64, v64, v78
	s_waitcnt lgkmcnt(1)
	v_add_f32_e32 v66, v66, v80
	ds_bpermute_b32 v71, v41, v60
	ds_bpermute_b32 v72, v41, v61
	ds_bpermute_b32 v73, v41, v62
	ds_bpermute_b32 v80, v41, v65
	v_mul_f32_e32 v48, v74, v48
	ds_bpermute_b32 v74, v41, v63
	ds_bpermute_b32 v78, v41, v64
	s_waitcnt lgkmcnt(6)
	v_add_f32_e32 v67, v67, v81
	v_add_f32_e32 v75, 1.0, v82
	v_add_f32_e32 v76, 1.0, v83
	s_waitcnt vmcnt(3)
	v_lshlrev_b32_e32 v79, 16, v46
	v_and_b32_e32 v46, 0xffff0000, v46
	ds_bpermute_b32 v81, v41, v66
	v_rcp_f32_e32 v75, v75
	v_rcp_f32_e32 v76, v76
	v_mul_f32_e32 v84, 0xbfb8aa3b, v46
	ds_bpermute_b32 v82, v41, v67
	v_mul_f32_e32 v83, 0xbfb8aa3b, v79
	v_exp_f32_e32 v84, v84
	v_exp_f32_e32 v83, v83
	s_waitcnt lgkmcnt(7)
	v_add_f32_e32 v60, v60, v71
	s_waitcnt lgkmcnt(6)
	v_add_f32_e32 v61, v61, v72
	s_waitcnt lgkmcnt(5)
	v_add_f32_e32 v62, v62, v73
	s_waitcnt lgkmcnt(4)
	v_add_f32_e32 v65, v65, v80
	s_waitcnt lgkmcnt(3)
	v_add_f32_e32 v63, v63, v74
	s_waitcnt lgkmcnt(2)
	v_add_f32_e32 v64, v64, v78
	ds_bpermute_b32 v72, v42, v60
	ds_bpermute_b32 v73, v42, v61
	ds_bpermute_b32 v74, v42, v62
	ds_bpermute_b32 v80, v42, v65
	v_mul_f32_e32 v71, v75, v77
	v_mul_f32_e32 v47, v76, v47
	s_waitcnt lgkmcnt(5)
	v_add_f32_e32 v66, v66, v81
	ds_bpermute_b32 v75, v42, v63
	ds_bpermute_b32 v76, v42, v64
	s_waitcnt vmcnt(2)
	v_lshlrev_b32_e32 v81, 16, v45
	v_and_b32_e32 v45, 0xffff0000, v45
	v_add_f32_e32 v78, 1.0, v84
	v_mul_f32_e32 v84, 0xbfb8aa3b, v81
	v_mul_f32_e32 v85, 0xbfb8aa3b, v45
	s_waitcnt lgkmcnt(6)
	v_add_f32_e32 v67, v67, v82
	v_add_f32_e32 v77, 1.0, v83
	v_exp_f32_e32 v84, v84
	v_exp_f32_e32 v85, v85
	ds_bpermute_b32 v83, v42, v67
	v_rcp_f32_e32 v77, v77
	ds_bpermute_b32 v82, v42, v66
	s_waitcnt lgkmcnt(7)
	v_add_f32_e32 v60, v60, v72
	s_waitcnt lgkmcnt(6)
	v_add_f32_e32 v61, v61, v73
	s_waitcnt lgkmcnt(5)
	v_add_f32_e32 v62, v62, v74
	s_waitcnt lgkmcnt(4)
	v_add_f32_e32 v65, v65, v80
	s_waitcnt lgkmcnt(3)
	v_add_f32_e32 v63, v63, v75
	s_waitcnt lgkmcnt(2)
	v_add_f32_e32 v64, v64, v76
	v_fmamk_f32 v60, v60, 0x3c000000, v43
	v_fmamk_f32 v61, v61, 0x3c000000, v43
	v_fmamk_f32 v62, v62, 0x3c000000, v43
	v_fmamk_f32 v65, v65, 0x3c000000, v43
	s_waitcnt vmcnt(1)
	v_lshlrev_b32_e32 v75, 16, v44
	v_fmamk_f32 v63, v63, 0x3c000000, v43
	v_fmamk_f32 v64, v64, 0x3c000000, v43
	v_add_f32_e32 v73, 1.0, v84
	v_add_f32_e32 v74, 1.0, v85
	v_and_b32_e32 v44, 0xffff0000, v44
	v_rsq_f32_e32 v60, v60
	v_rsq_f32_e32 v61, v61
	v_rsq_f32_e32 v62, v62
	v_rsq_f32_e32 v65, v65
	v_mul_f32_e32 v76, 0xbfb8aa3b, v75
	v_mul_f32_e32 v72, v77, v79
	v_rsq_f32_e32 v63, v63
	v_rsq_f32_e32 v64, v64
	v_rcp_f32_e32 v73, v73
	v_rcp_f32_e32 v74, v74
	v_mul_f32_e32 v77, 0xbfb8aa3b, v44
	v_exp_f32_e32 v76, v76
	s_waitcnt lgkmcnt(1)
	v_add_f32_e32 v67, v67, v83
	v_exp_f32_e32 v77, v77
	v_rcp_f32_e32 v78, v78
	s_waitcnt lgkmcnt(0)
	v_add_f32_e32 v66, v66, v82
	v_fmamk_f32 v67, v67, 0x3c000000, v43
	v_fmamk_f32 v66, v66, 0x3c000000, v43
	v_rsq_f32_e32 v67, v67
	v_mul_f32_e32 v51, v60, v51
	v_mul_f32_e32 v0, v61, v0
	v_mul_f32_e32 v4, v61, v4
	v_mul_f32_e32 v54, v62, v54
	v_mul_f32_e32 v2, v65, v2
	v_mul_f32_e32 v6, v65, v6
	v_rsq_f32_e32 v66, v66
	v_mul_f32_e32 v53, v60, v53
	v_mul_f32_e32 v55, v62, v55
	v_mul_f32_e32 v1, v63, v1
	v_mul_f32_e32 v5, v63, v5
	v_mul_f32_e32 v56, v64, v56
	v_mul_f32_e32 v60, v73, v81
	v_mul_f32_e32 v45, v74, v45
	v_mul_f32_e32 v51, v8, v51
	v_mul_f32_e32 v0, v8, v0
	v_mul_f32_e32 v4, v9, v4
	v_mul_f32_e32 v54, v8, v54
	v_mul_f32_e32 v2, v8, v2
	v_mul_f32_e32 v6, v9, v6
	v_add_f32_e32 v61, 1.0, v76
	s_waitcnt vmcnt(0)
	v_lshlrev_b32_e32 v63, 16, v50
	v_mul_f32_e32 v57, v64, v57
	v_mul_f32_e32 v53, v9, v53
	v_mul_f32_e32 v55, v9, v55
	v_mul_f32_e32 v1, v8, v1
	v_mul_f32_e32 v5, v9, v5
	v_mul_f32_e32 v56, v8, v56
	v_add_f32_e32 v62, 1.0, v77
	v_and_b32_e32 v50, 0xffff0000, v50
	v_mul_f32_e32 v51, v68, v51
	v_mul_f32_e32 v0, v69, v0
	v_mul_f32_e32 v4, v49, v4
	v_mul_f32_e32 v49, v70, v54
	v_mul_f32_e32 v2, v60, v2
	v_mul_f32_e32 v6, v45, v6
	v_rcp_f32_e32 v45, v61
	v_mul_f32_e32 v54, 0xbfb8aa3b, v63
	v_mul_f32_e32 v46, v78, v46
	v_mul_f32_e32 v57, v9, v57
	v_mul_f32_e32 v52, v52, v53
	v_mul_f32_e32 v48, v48, v55
	v_mul_f32_e32 v1, v71, v1
	v_mul_f32_e32 v5, v47, v5
	v_mul_f32_e32 v47, v72, v56
	v_rcp_f32_e32 v53, v62
	v_mul_f32_e32 v55, 0xbfb8aa3b, v50
	v_bfe_u32 v56, v51, 16, 1
	v_bfe_u32 v60, v0, 16, 1
	v_bfe_u32 v69, v2, 16, 1
	v_exp_f32_e32 v54, v54
	v_mul_f32_e32 v3, v67, v3
	v_mul_f32_e32 v7, v67, v7
	v_mul_f32_e32 v46, v46, v57
	v_bfe_u32 v57, v52, 16, 1
	v_bfe_u32 v61, v4, 16, 1
	v_bfe_u32 v62, v49, 16, 1
	v_bfe_u32 v65, v1, 16, 1
	v_bfe_u32 v67, v47, 16, 1
	v_bfe_u32 v70, v6, 16, 1
	v_exp_f32_e32 v55, v55
	v_add3_u32 v51, v51, v56, s30
	v_add3_u32 v0, v0, v60, s30
	v_add3_u32 v2, v2, v69, s30
	s_mov_b32 s27, s25
	s_mov_b32 s23, s25
	s_mov_b32 s19, s25
	s_mov_b32 s17, s25
	s_mov_b32 s15, s25
	s_mov_b32 s13, s25
	s_mov_b32 s11, s25
	s_lshl_b64 s[24:25], s[24:25], 11
	v_mul_f32_e32 v58, v66, v58
	v_mul_f32_e32 v59, v66, v59
	v_bfe_u32 v64, v48, 16, 1
	v_bfe_u32 v66, v5, 16, 1
	v_bfe_u32 v68, v46, 16, 1
	v_add3_u32 v52, v52, v57, s30
	v_add3_u32 v4, v4, v61, s30
	v_add3_u32 v49, v49, v62, s30
	v_add3_u32 v1, v1, v65, s30
	v_add3_u32 v47, v47, v67, s30
	v_add3_u32 v6, v6, v70, s30
	v_lshrrev_b32_e32 v51, 16, v51
	v_lshrrev_b32_e32 v0, 16, v0
	v_lshrrev_b32_e32 v2, 16, v2
	s_lshl_b64 s[26:27], s[26:27], 11
	s_lshl_b64 s[22:23], s[22:23], 11
	s_lshl_b64 s[18:19], s[18:19], 11
	s_lshl_b64 s[16:17], s[16:17], 11
	s_lshl_b64 s[14:15], s[14:15], 11
	v_lshl_add_u64 v[24:25], v[20:21], 0, s[24:25]
	v_mul_f32_e32 v58, v8, v58
	v_add3_u32 v48, v48, v64, s30
	v_add3_u32 v5, v5, v66, s30
	v_add3_u32 v46, v46, v68, s30
	v_lshrrev_b32_e32 v49, 16, v49
	v_lshrrev_b32_e32 v1, 16, v1
	v_lshrrev_b32_e32 v47, 16, v47
	v_and_or_b32 v51, v52, s29, v51
	v_and_or_b32 v0, v4, s29, v0
	v_and_or_b32 v2, v6, s29, v2
	v_mul_f32_e32 v6, v45, v75
	v_lshl_add_u64 v[26:27], v[20:21], 0, s[26:27]
	v_lshl_add_u64 v[28:29], v[20:21], 0, s[22:23]
	v_lshl_add_u64 v[30:31], v[20:21], 0, s[18:19]
	v_lshl_add_u64 v[32:33], v[20:21], 0, s[16:17]
	v_lshl_add_u64 v[34:35], v[20:21], 0, s[14:15]
	v_mul_f32_e32 v59, v9, v59
	v_and_or_b32 v4, v48, s29, v49
	v_and_or_b32 v1, v5, s29, v1
	v_and_or_b32 v5, v46, s29, v47
	v_mul_f32_e32 v44, v53, v44
	global_store_dword v[24:25], v51, off
	global_store_dword v[26:27], v0, off
	global_store_dword v[28:29], v4, off
	global_store_dword v[30:31], v1, off
	global_store_dword v[32:33], v5, off
	global_store_dword v[34:35], v2, off
	v_mul_f32_e32 v0, v6, v58
	v_add_f32_e32 v2, 1.0, v54
	v_mul_f32_e32 v1, v44, v59
	v_add_f32_e32 v4, 1.0, v55
	v_bfe_u32 v5, v0, 16, 1
	v_rcp_f32_e32 v2, v2
	v_bfe_u32 v6, v1, 16, 1
	v_rcp_f32_e32 v4, v4
	v_add3_u32 v0, v0, v5, s30
	s_lshl_b64 s[12:13], s[12:13], 11
	v_add3_u32 v1, v1, v6, s30
	v_lshrrev_b32_e32 v0, 16, v0
	v_lshl_add_u64 v[22:23], v[20:21], 0, s[12:13]
	v_and_or_b32 v0, v1, s29, v0
	v_mul_f32_e32 v3, v8, v3
	global_store_dword v[22:23], v0, off
	v_mul_f32_e32 v0, v2, v63
	s_lshl_b64 s[10:11], s[10:11], 11
	v_mul_f32_e32 v7, v9, v7
	v_mul_f32_e32 v1, v4, v50
	v_mul_f32_e32 v0, v0, v3
	s_add_u32 s4, s4, s78
	v_mul_f32_e32 v1, v1, v7
	v_bfe_u32 v2, v0, 16, 1
	s_addc_u32 s5, s5, s0
	v_bfe_u32 v3, v1, 16, 1
	v_add3_u32 v0, v0, v2, s30
	v_cmp_lt_i64_e32 vcc, s[4:5], v[18:19]
	v_add3_u32 v1, v1, v3, s30
	v_lshrrev_b32_e32 v0, 16, v0
	v_lshl_add_u64 v[20:21], v[20:21], 0, s[10:11]
	v_and_or_b32 v0, v1, s29, v0
	global_store_dword v[20:21], v0, off
	s_cbranch_vccnz .LBB0_2592
